# v52 with the static priority for waves 4-7 raised from 1 to 3
# baseline (speedup 1.0000x reference)
; __global__ void __launch_bounds__(512) mega(Params p) {
;   cg::grid_group grid = cg::this_grid();
;   phase_init(p);
;   Ctx c; c.out = p.out; c.ws = p.ws; c.wv = __builtin_amdgcn_readfirstlane((int)(threadIdx.x >> 6)); c.bid = blockIdx.x; c.nb = gridDim.x;
_Z4mega6Params:
	v_readfirstlane_b32 s100, v0
	s_bitcmp1_b32 s100, 8
	s_cbranch_scc0 .Lprio_skip
	s_setprio 3
